# v28 + grid barrier: the second-to-last arriver of each XCD starts an L2 writeback early
# baseline (speedup 1.0000x reference)
.LBB0_536:
	v_readlane_b32 s4, v253, 48
	v_readlane_b32 s5, v253, 49
	v_cvt_f32_u32_e32 v1, v2
	v_sub_u32_e32 v4, 0, v2
	v_rcp_iflag_f32_e32 v1, v1
	s_nop 1
	global_atomic_add v3, v64, v216, s[4:5] sc0
	buffer_inv sc1
	v_mul_f32_e32 v1, 0x4f7ffffe, v1
	v_cvt_u32_f32_e32 v1, v1
	v_mul_lo_u32 v4, v4, v1
	v_mul_hi_u32 v4, v1, v4
	v_add_u32_e32 v1, v1, v4
	s_waitcnt vmcnt(1)
	v_mul_hi_u32 v1, v3, v1
	v_mul_lo_u32 v4, v1, v2
	v_sub_u32_e32 v4, v3, v4
	v_add_u32_e32 v5, 1, v1
	v_cmp_ge_u32_e32 vcc, v4, v2
	v_add_u32_e32 v3, 1, v3
	s_nop 0
	v_cndmask_b32_e32 v1, v1, v5, vcc
	v_sub_u32_e32 v5, v4, v2
	v_cndmask_b32_e32 v4, v4, v5, vcc
	v_add_u32_e32 v5, 1, v1
	v_cmp_ge_u32_e32 vcc, v4, v2
	s_nop 1
	v_cndmask_b32_e32 v1, v1, v5, vcc
	v_mul_lo_u32 v4, v2, v1
	v_add_u32_e32 v2, v4, v2
	v_cmp_ne_u32_e32 vcc, v3, v2
	s_and_saveexec_b64 s[4:5], vcc
	s_xor_b64 s[4:5], exec, s[4:5]
	s_cbranch_execz .LBB0_550
	v_add_u32_e32 v4, 1, v3
	v_cmp_ne_u32_e32 vcc, v4, v2
	s_cbranch_vccnz .Lxb_skip0
	buffer_wbl2 sc1
.Lxb_skip0:
	v_readlane_b32 s6, v253, 50
	v_readlane_b32 s7, v253, 51
	s_waitcnt lgkmcnt(0)
	s_nop 3
	global_load_dword v0, v64, s[6:7] sc1
	s_waitcnt vmcnt(0)
	v_cmp_eq_u32_e32 vcc, v0, v1
	s_and_saveexec_b64 s[6:7], vcc
	s_cbranch_execz .LBB0_549
	s_mov_b32 s12, 1
	s_mov_b64 s[8:9], 0
	s_branch .LBB0_540

.Lxb_skip1:
	v_readlane_b32 s6, v253, 50
	v_readlane_b32 s7, v253, 51
	s_waitcnt lgkmcnt(0)
	s_nop 3
	global_load_dword v0, v64, s[6:7] sc1
	s_waitcnt vmcnt(0)
	v_cmp_eq_u32_e32 vcc, v0, v1
	s_and_saveexec_b64 s[6:7], vcc
	s_cbranch_execz .LBB0_629
	s_mov_b32 s13, 1
	s_mov_b64 s[8:9], 0
	s_branch .LBB0_620
